# blocked HID layout [mtile][kblock][128][64] between ffn1 and ffn2 so each ffn2 A stage is a contiguous 16KB (plus ffn2 K-rotation)
# baseline (speedup 1.0000x reference)
.LBB0_126:
	s_lshr_b32 s15, s14, 3
	v_mov_b32_e32 v6, v254
	s_and_b32 s16, s15, 0xffffff8
	s_and_b32 s15, s14, 7
	v_ashrrev_i32_e32 v0, 3, v6
	s_lshl_b32 s83, s16, 7
	s_lshl_b32 s14, s14, 4
	v_xor_b32_e32 v5, v0, v6
	s_sub_i32 s14, s14, s83
	v_lshlrev_b32_e32 v1, 3, v5
	s_and_b32 s22, s14, 0xffffff80
	v_and_b32_e32 v7, 56, v1
	v_ashrrev_i32_e32 v1, 31, v0
	s_or_b32 s17, s16, s15
	s_ashr_i32 s23, s22, 31
	v_lshlrev_b64 v[2:3], 12, v[0:1]
	s_lshl_b32 s26, s17, 7
	s_lshl_b64 s[36:37], s[22:23], 13
	s_mov_b64 s[16:17], -1
	s_and_b64 vcc, exec, s[40:41]
	v_lshlrev_b64 v[2:3], 1, v[2:3]
	v_lshlrev_b32_e32 v148, 1, v7
	v_lshlrev_b32_e32 v7, 4, v6
	s_cbranch_vccz .LBB0_128
	s_lshl_b64 s[16:17], s[26:27], 13
	s_add_u32 s16, s25, s16
	s_addc_u32 s17, s33, s17
	s_lshl_b32 s14, s26, 8
	s_and_b32 s14, s14, 0x38000
	s_add_u32 s16, s16, s14
	s_addc_u32 s17, s17, 0
	v_lshlrev_b32_e32 v85, 4, v6
	s_add_u32 s40, s44, s36
	s_addc_u32 s41, s45, s37
	s_lshl_b32 s84, s26, 1
	s_and_b32 s84, s84, 0x700
	s_add_u32 s40, s40, s84
	s_addc_u32 s41, s41, 0
	v_lshrrev_b32_e32 v12, 6, v2
	v_mov_b32_e32 v13, 0
	v_lshl_add_u64 v[8:9], s[16:17], 0, v[12:13]
	v_lshl_add_u64 v[8:9], v[8:9], 0, v[148:149]
	v_lshl_add_u64 v[10:11], s[40:41], 0, v[2:3]
	v_lshl_add_u64 v[10:11], v[10:11], 0, v[148:149]
	v_readfirstlane_b32 s14, v85
	s_mov_b32 m0, s14
	s_mov_b64 s[16:17], 0x1000
	s_mov_b64 s[40:41], 0x40000
	s_barrier
	global_load_lds_dwordx4 v[8:9], off
	s_add_u32 m0, m0, 0x1000
	v_lshl_add_u64 v[8:9], v[8:9], 0, s[16:17]
	global_load_lds_dwordx4 v[8:9], off
	s_add_u32 m0, m0, 0x1000
	v_lshl_add_u64 v[8:9], v[8:9], 0, s[16:17]
	global_load_lds_dwordx4 v[8:9], off
	s_add_u32 m0, m0, 0x1000
	v_lshl_add_u64 v[8:9], v[8:9], 0, s[16:17]
	global_load_lds_dwordx4 v[8:9], off
	s_add_u32 m0, m0, 0x1000
	s_nop 0
	global_load_lds_dwordx4 v[10:11], off
	s_add_u32 m0, m0, 0x1000
	v_lshl_add_u64 v[10:11], v[10:11], 0, s[40:41]
	global_load_lds_dwordx4 v[10:11], off
	s_add_u32 m0, m0, 0x1000
	v_lshl_add_u64 v[10:11], v[10:11], 0, s[40:41]
	global_load_lds_dwordx4 v[10:11], off
	s_add_u32 m0, m0, 0x1000
	v_lshl_add_u64 v[10:11], v[10:11], 0, s[40:41]
	global_load_lds_dwordx4 v[10:11], off
	s_mov_b64 s[16:17], 0

.LBB0_130:
	s_add_u32 s14, s25, s30
	v_cmp_lt_i32_e32 vcc, -1, v4
	s_addc_u32 s17, s33, s31
	s_and_b64 s[30:31], vcc, exec
	v_lshrrev_b32_e32 v7, 4, v6
	v_and_b32_e32 v9, 7, v6
	s_cselect_b32 s31, s17, 0
	s_cselect_b32 s30, s14, 0
	s_add_u32 s28, s44, s28
	v_bfe_u32 v8, v6, 4, 2
	v_bitop3_b32 v7, v7, v9, 3 bitop3:0x6c
	s_addc_u32 s29, s45, s29
	v_lshlrev_b32_e32 v86, 4, v7
	v_bitop3_b32 v7, v8, v9, 4 bitop3:0x36
	v_and_b32_e32 v4, 15, v6
	v_lshlrev_b32_e32 v87, 4, v7
	v_lshrrev_b32_e32 v7, 1, v6
	s_cmp_lg_u64 s[30:31], 0
	v_and_or_b32 v4, v7, s47, v4
	v_lshl_add_u64 v[8:9], s[30:31], 0, v[148:149]
	s_cselect_b64 s[30:31], -1, 0
	s_lshl_b32 s14, s15, 7
	v_lshlrev_b32_e32 v88, 7, v4
	v_lshlrev_b32_e32 v4, 7, v6
	s_add_i32 s14, s83, s14
	s_mov_b32 s15, s27
	v_and_b32_e32 v89, 0x2780, v4
	v_lshl_add_u64 v[6:7], s[28:29], 0, v[148:149]
	v_lshlrev_b64 v[0:1], 13, v[0:1]
	v_lshlrev_b32_e32 v4, 4, v5
	s_lshl_b64 s[14:15], s[14:15], 13
	v_lshrrev_b32_e32 v10, 6, v2
	v_mov_b32_e32 v11, 0
	v_lshl_add_u64 v[64:65], v[8:9], 0, v[10:11]
	v_lshl_add_u64 v[66:67], v[6:7], 0, v[2:3]
	s_and_b32 s16, s56, 7
	s_lshl_b32 s16, s16, 8
	v_mov_b32_e32 v10, s16
	v_lshl_add_u64 v[66:67], v[66:67], 0, v[10:11]
	s_lshl_b32 s16, s16, 7
	v_mov_b32_e32 v10, s16
	v_lshl_add_u64 v[64:65], v[64:65], 0, v[10:11]
	v_lshl_add_u64 v[2:3], v[0:1], 0, s[36:37]
	v_lshrrev_b64 v[0:1], 6, v[0:1]
	v_and_b32_e32 v148, 0x70, v4
	v_lshl_add_u64 v[0:1], v[0:1], 0, s[14:15]
	s_mov_b64 s[40:41], 0x40000
	s_mov_b64 s[84:85], 0x80000
	s_mov_b64 s[86:87], 0xc0000
	v_lshl_add_u64 v[2:3], v[2:3], 0, v[148:149]
	v_or_b32_e32 v0, v0, v148
	v_mov_b32_e32 v56, 0
	s_mov_b32 s16, 0
	s_mov_b64 s[28:29], 0
	v_mov_b32_e32 v10, 0x1000
	v_lshl_add_u64 v[68:69], v[64:65], 0, v[10:11]
	v_lshl_add_u64 v[70:71], v[68:69], 0, v[10:11]
	v_lshl_add_u64 v[72:73], v[70:71], 0, v[10:11]
	v_lshl_add_u64 v[74:75], v[66:67], 0, s[40:41]
	v_lshl_add_u64 v[76:77], v[66:67], 0, s[84:85]
	v_lshl_add_u64 v[78:79], v[66:67], 0, s[86:87]
	v_lshl_add_u64 v[80:81], s[10:11], 0, v[2:3]
	v_lshl_add_u64 v[82:83], s[10:11], 0, v[0:1]
	s_mov_b32 s17, 0
	v_mov_b32_e32 v57, v56
	v_mov_b32_e32 v58, v56
	v_mov_b32_e32 v59, v56
	v_mov_b32_e32 v0, v56
	v_mov_b32_e32 v1, v56
	v_mov_b32_e32 v2, v56
	v_mov_b32_e32 v3, v56
	v_mov_b32_e32 v4, v56
	v_mov_b32_e32 v5, v56
	v_mov_b32_e32 v6, v56
	v_mov_b32_e32 v7, v56
	v_mov_b32_e32 v8, v56
	v_mov_b32_e32 v9, v56
	v_mov_b32_e32 v10, v56
	v_mov_b32_e32 v11, v56
	v_mov_b32_e32 v12, v56
	v_mov_b32_e32 v13, v56
	v_mov_b32_e32 v14, v56
	v_mov_b32_e32 v15, v56
	v_mov_b32_e32 v16, v56
	v_mov_b32_e32 v17, v56
	v_mov_b32_e32 v18, v56
	v_mov_b32_e32 v19, v56
	v_mov_b32_e32 v20, v56
	v_mov_b32_e32 v21, v56
	v_mov_b32_e32 v22, v56
	v_mov_b32_e32 v23, v56
	v_mov_b32_e32 v24, v56
	v_mov_b32_e32 v25, v56
	v_mov_b32_e32 v26, v56
	v_mov_b32_e32 v27, v56
	v_mov_b32_e32 v28, v56
	v_mov_b32_e32 v29, v56
	v_mov_b32_e32 v30, v56
	v_mov_b32_e32 v31, v56
	v_mov_b32_e32 v32, v56
	v_mov_b32_e32 v33, v56
	v_mov_b32_e32 v34, v56
	v_mov_b32_e32 v35, v56
	v_mov_b32_e32 v36, v56
	v_mov_b32_e32 v37, v56
	v_mov_b32_e32 v38, v56
	v_mov_b32_e32 v39, v56
	s_waitcnt vmcnt(0)
	v_mov_b32_e32 v40, v56
	v_mov_b32_e32 v41, v56
	v_mov_b32_e32 v42, v56
	v_mov_b32_e32 v43, v56
	v_mov_b32_e32 v44, v56
	v_mov_b32_e32 v45, v56
	v_mov_b32_e32 v46, v56
	v_mov_b32_e32 v47, v56
	v_mov_b32_e32 v48, v56
	v_mov_b32_e32 v49, v56
	v_mov_b32_e32 v50, v56
	v_mov_b32_e32 v51, v56
	v_mov_b32_e32 v52, v56
	v_mov_b32_e32 v53, v56
	v_mov_b32_e32 v54, v56
	v_mov_b32_e32 v55, v56
	v_mov_b32_e32 v60, v56
	v_mov_b32_e32 v61, v56
	v_mov_b32_e32 v62, v56
	v_mov_b32_e32 v63, v56
	s_branch .LBB0_132

.LBB0_136:
	s_andn2_b64 vcc, exec, s[14:15]
	s_cbranch_vccnz .LBB0_131
	s_add_i32 s14, s16, 0x8000
	s_and_b32 s14, s14, 0x8000
	v_add_u32_e32 v94, s14, v85
	s_lshl_b32 s15, s26, 1
	s_and_b32 s15, s15, 0x700
	v_readfirstlane_b32 s14, v94
	s_mov_b32 m0, s14
	s_add_u32 s14, s15, s28
	s_add_u32 s14, s14, 0x80
	s_and_b32 s14, s14, 0x1fff
	s_mov_b32 s15, 0
	s_add_u32 s14, s14, 0xa01000
	v_lshl_add_u64 v[90:91], v[80:81], 0, s[14:15]
	s_sub_u32 s14, s14, 0xa01000
	s_lshl_b32 s14, s14, 7
	s_add_u32 s14, s14, 0x1201000
	v_lshl_add_u64 v[92:93], v[82:83], 0, s[14:15]
	s_mov_b64 s[14:15], 0x1000
	global_load_lds_dwordx4 v[92:93], off
	s_add_u32 m0, m0, 0x1000
	v_lshl_add_u64 v[92:93], v[92:93], 0, s[14:15]
	global_load_lds_dwordx4 v[92:93], off
	s_add_u32 m0, m0, 0x1000
	v_lshl_add_u64 v[92:93], v[92:93], 0, s[14:15]
	global_load_lds_dwordx4 v[92:93], off
	s_add_u32 m0, m0, 0x1000
	v_lshl_add_u64 v[92:93], v[92:93], 0, s[14:15]
	global_load_lds_dwordx4 v[92:93], off
	s_add_u32 m0, m0, 0x1000
	s_nop 0
	global_load_lds_dwordx4 v[90:91], off
	s_add_u32 m0, m0, 0x1000
	v_lshl_add_u64 v[90:91], v[90:91], 0, s[40:41]
	global_load_lds_dwordx4 v[90:91], off
	s_add_u32 m0, m0, 0x1000
	v_lshl_add_u64 v[90:91], v[90:91], 0, s[40:41]
	global_load_lds_dwordx4 v[90:91], off
	s_add_u32 m0, m0, 0x1000
	v_lshl_add_u64 v[90:91], v[90:91], 0, s[40:41]
	global_load_lds_dwordx4 v[90:91], off
	s_branch .LBB0_131

.LBB0_177:
	v_mov_b32_e32 v64, v254
	s_waitcnt vmcnt(0)
	s_barrier
	s_nop 1
	v_max_f32_e32 v0, v0, v0
	v_lshrrev_b32_e32 v66, 2, v64
	v_lshrrev_b32_e32 v65, 1, v64
	v_and_b32_e32 v66, 12, v66
	v_and_or_b32 v65, v65, s49, v66
	v_max_f32_e32 v0, 0, v0
	v_and_b32_e32 v64, 0x4f, v64
	v_mul_lo_u32 v65, v65, s42
	v_mul_f32_e32 v0, v0, v0
	v_lshl_add_u32 v64, v64, 1, v65
	v_cvt_pk_bf16_f32 v0, v0, s0
	ds_write_b16 v64, v0 offset:45856
	v_max_f32_e32 v0, v1, v1
	v_max_f32_e32 v0, 0, v0
	v_mul_f32_e32 v0, v0, v0
	v_cvt_pk_bf16_f32 v0, v0, s0
	ds_write_b16 v64, v0 offset:46128
	v_max_f32_e32 v0, v2, v2
	v_max_f32_e32 v0, 0, v0
	v_mul_f32_e32 v0, v0, v0
	v_cvt_pk_bf16_f32 v0, v0, s0
	ds_write_b16 v64, v0 offset:46400
	v_max_f32_e32 v0, v3, v3
	v_max_f32_e32 v0, 0, v0
	v_mul_f32_e32 v0, v0, v0
	v_cvt_pk_bf16_f32 v0, v0, s0
	ds_write_b16 v64, v0 offset:46672
	v_max_f32_e32 v0, v12, v12
	v_max_f32_e32 v0, 0, v0
	v_mul_f32_e32 v0, v0, v0
	v_cvt_pk_bf16_f32 v0, v0, s0
	ds_write_b16 v64, v0 offset:45888
	v_max_f32_e32 v0, v13, v13
	v_max_f32_e32 v0, 0, v0
	v_mul_f32_e32 v0, v0, v0
	v_cvt_pk_bf16_f32 v0, v0, s0
	ds_write_b16 v64, v0 offset:46160
	v_max_f32_e32 v0, v14, v14
	v_max_f32_e32 v0, 0, v0
	v_mul_f32_e32 v0, v0, v0
	v_cvt_pk_bf16_f32 v0, v0, s0
	ds_write_b16 v64, v0 offset:46432
	v_max_f32_e32 v0, v15, v15
	v_max_f32_e32 v0, 0, v0
	v_mul_f32_e32 v0, v0, v0
	v_cvt_pk_bf16_f32 v0, v0, s0
	v_max_f32_e32 v60, v60, v60
	v_max_f32_e32 v56, v56, v56
	v_max_f32_e32 v52, v52, v52
	v_max_f32_e32 v48, v48, v48
	v_max_f32_e32 v44, v44, v44
	v_max_f32_e32 v40, v40, v40
	v_max_f32_e32 v36, v36, v36
	v_max_f32_e32 v32, v32, v32
	v_max_f32_e32 v28, v28, v28
	v_max_f32_e32 v24, v24, v24
	v_max_f32_e32 v20, v20, v20
	v_max_f32_e32 v16, v16, v16
	v_max_f32_e32 v8, v8, v8
	ds_write_b16 v64, v0 offset:46704
	v_max_f32_e32 v0, v4, v4
	v_max_f32_e32 v60, 0, v60
	v_max_f32_e32 v56, 0, v56
	v_max_f32_e32 v52, 0, v52
	v_max_f32_e32 v48, 0, v48
	v_max_f32_e32 v44, 0, v44
	v_max_f32_e32 v40, 0, v40
	v_max_f32_e32 v36, 0, v36
	v_max_f32_e32 v32, 0, v32
	v_max_f32_e32 v28, 0, v28
	v_max_f32_e32 v24, 0, v24
	v_max_f32_e32 v20, 0, v20
	v_max_f32_e32 v16, 0, v16
	v_max_f32_e32 v8, 0, v8
	v_max_f32_e32 v0, 0, v0
	v_mul_f32_e32 v60, v60, v60
	v_mul_f32_e32 v56, v56, v56
	v_mul_f32_e32 v52, v52, v52
	v_mul_f32_e32 v48, v48, v48
	v_mul_f32_e32 v44, v44, v44
	v_mul_f32_e32 v40, v40, v40
	v_mul_f32_e32 v36, v36, v36
	v_mul_f32_e32 v32, v32, v32
	v_mul_f32_e32 v28, v28, v28
	v_mul_f32_e32 v24, v24, v24
	v_mul_f32_e32 v20, v20, v20
	v_mul_f32_e32 v16, v16, v16
	v_mul_f32_e32 v8, v8, v8
	v_mul_f32_e32 v0, v0, v0
	v_cvt_pk_bf16_f32 v60, v60, s0
	v_cvt_pk_bf16_f32 v56, v56, s0
	v_cvt_pk_bf16_f32 v52, v52, s0
	v_cvt_pk_bf16_f32 v48, v48, s0
	v_cvt_pk_bf16_f32 v44, v44, s0
	v_cvt_pk_bf16_f32 v40, v40, s0
	v_cvt_pk_bf16_f32 v36, v36, s0
	v_cvt_pk_bf16_f32 v32, v32, s0
	v_cvt_pk_bf16_f32 v28, v28, s0
	v_cvt_pk_bf16_f32 v24, v24, s0
	v_cvt_pk_bf16_f32 v20, v20, s0
	v_cvt_pk_bf16_f32 v16, v16, s0
	v_cvt_pk_bf16_f32 v8, v8, s0
	v_cvt_pk_bf16_f32 v0, v0, s0
	ds_write_b16 v64, v60 offset:32768
	v_max_f32_e32 v60, v61, v61
	ds_write_b16 v64, v56 offset:32800
	v_max_f32_e32 v56, v57, v57
	ds_write_b16 v64, v52 offset:32832
	v_max_f32_e32 v52, v53, v53
	ds_write_b16 v64, v48 offset:32864
	v_max_f32_e32 v48, v49, v49
	ds_write_b16 v64, v44 offset:37120
	v_max_f32_e32 v44, v45, v45
	ds_write_b16 v64, v40 offset:37152
	v_max_f32_e32 v40, v41, v41
	ds_write_b16 v64, v36 offset:37184
	v_max_f32_e32 v36, v37, v37
	ds_write_b16 v64, v32 offset:37216
	v_max_f32_e32 v32, v33, v33
	ds_write_b16 v64, v28 offset:41472
	v_max_f32_e32 v28, v29, v29
	ds_write_b16 v64, v24 offset:41504
	v_max_f32_e32 v24, v25, v25
	ds_write_b16 v64, v20 offset:41536
	v_max_f32_e32 v20, v21, v21
	ds_write_b16 v64, v16 offset:41568
	v_max_f32_e32 v16, v17, v17
	ds_write_b16 v64, v8 offset:45824
	v_max_f32_e32 v8, v9, v9
	ds_write_b16 v64, v0 offset:45920
	v_max_f32_e32 v0, v5, v5
	v_max_f32_e32 v60, 0, v60
	v_max_f32_e32 v56, 0, v56
	v_max_f32_e32 v52, 0, v52
	v_max_f32_e32 v48, 0, v48
	v_max_f32_e32 v44, 0, v44
	v_max_f32_e32 v40, 0, v40
	v_max_f32_e32 v36, 0, v36
	v_max_f32_e32 v32, 0, v32
	v_max_f32_e32 v28, 0, v28
	v_max_f32_e32 v24, 0, v24
	v_max_f32_e32 v20, 0, v20
	v_max_f32_e32 v16, 0, v16
	v_max_f32_e32 v8, 0, v8
	v_max_f32_e32 v0, 0, v0
	v_mul_f32_e32 v60, v60, v60
	v_mul_f32_e32 v56, v56, v56
	v_mul_f32_e32 v52, v52, v52
	v_mul_f32_e32 v48, v48, v48
	v_mul_f32_e32 v44, v44, v44
	v_mul_f32_e32 v40, v40, v40
	v_mul_f32_e32 v36, v36, v36
	v_mul_f32_e32 v32, v32, v32
	v_mul_f32_e32 v28, v28, v28
	v_mul_f32_e32 v24, v24, v24
	v_mul_f32_e32 v20, v20, v20
	v_mul_f32_e32 v16, v16, v16
	v_mul_f32_e32 v8, v8, v8
	v_mul_f32_e32 v0, v0, v0
	v_cvt_pk_bf16_f32 v60, v60, s0
	v_cvt_pk_bf16_f32 v56, v56, s0
	v_cvt_pk_bf16_f32 v52, v52, s0
	v_cvt_pk_bf16_f32 v48, v48, s0
	v_cvt_pk_bf16_f32 v44, v44, s0
	v_cvt_pk_bf16_f32 v40, v40, s0
	v_cvt_pk_bf16_f32 v36, v36, s0
	v_cvt_pk_bf16_f32 v32, v32, s0
	v_cvt_pk_bf16_f32 v28, v28, s0
	v_cvt_pk_bf16_f32 v24, v24, s0
	v_cvt_pk_bf16_f32 v20, v20, s0
	v_cvt_pk_bf16_f32 v16, v16, s0
	v_cvt_pk_bf16_f32 v8, v8, s0
	v_cvt_pk_bf16_f32 v0, v0, s0
	ds_write_b16 v64, v60 offset:33040
	v_max_f32_e32 v60, v62, v62
	ds_write_b16 v64, v56 offset:33072
	v_max_f32_e32 v56, v58, v58
	ds_write_b16 v64, v52 offset:33104
	v_max_f32_e32 v52, v54, v54
	ds_write_b16 v64, v48 offset:33136
	v_max_f32_e32 v48, v50, v50
	ds_write_b16 v64, v44 offset:37392
	v_max_f32_e32 v44, v46, v46
	ds_write_b16 v64, v40 offset:37424
	v_max_f32_e32 v40, v42, v42
	ds_write_b16 v64, v36 offset:37456
	v_max_f32_e32 v36, v38, v38
	ds_write_b16 v64, v32 offset:37488
	v_max_f32_e32 v32, v34, v34
	ds_write_b16 v64, v28 offset:41744
	v_max_f32_e32 v28, v30, v30
	ds_write_b16 v64, v24 offset:41776
	v_max_f32_e32 v24, v26, v26
	ds_write_b16 v64, v20 offset:41808
	v_max_f32_e32 v20, v22, v22
	ds_write_b16 v64, v16 offset:41840
	v_max_f32_e32 v16, v18, v18
	ds_write_b16 v64, v8 offset:46096
	v_max_f32_e32 v8, v10, v10
	ds_write_b16 v64, v0 offset:46192
	v_max_f32_e32 v0, v6, v6
	v_max_f32_e32 v60, 0, v60
	v_max_f32_e32 v56, 0, v56
	v_max_f32_e32 v52, 0, v52
	v_max_f32_e32 v48, 0, v48
	v_max_f32_e32 v44, 0, v44
	v_max_f32_e32 v40, 0, v40
	v_max_f32_e32 v36, 0, v36
	v_max_f32_e32 v32, 0, v32
	v_max_f32_e32 v28, 0, v28
	v_max_f32_e32 v24, 0, v24
	v_max_f32_e32 v20, 0, v20
	v_max_f32_e32 v16, 0, v16
	v_max_f32_e32 v8, 0, v8
	v_max_f32_e32 v0, 0, v0
	v_mul_f32_e32 v60, v60, v60
	v_mul_f32_e32 v56, v56, v56
	v_mul_f32_e32 v52, v52, v52
	v_mul_f32_e32 v48, v48, v48
	v_mul_f32_e32 v44, v44, v44
	v_mul_f32_e32 v40, v40, v40
	v_mul_f32_e32 v36, v36, v36
	v_mul_f32_e32 v32, v32, v32
	v_mul_f32_e32 v28, v28, v28
	v_mul_f32_e32 v24, v24, v24
	v_mul_f32_e32 v20, v20, v20
	v_mul_f32_e32 v16, v16, v16
	v_mul_f32_e32 v8, v8, v8
	v_mul_f32_e32 v0, v0, v0
	v_cvt_pk_bf16_f32 v60, v60, s0
	v_cvt_pk_bf16_f32 v56, v56, s0
	v_cvt_pk_bf16_f32 v52, v52, s0
	v_cvt_pk_bf16_f32 v48, v48, s0
	v_cvt_pk_bf16_f32 v44, v44, s0
	v_cvt_pk_bf16_f32 v40, v40, s0
	v_cvt_pk_bf16_f32 v36, v36, s0
	v_cvt_pk_bf16_f32 v32, v32, s0
	v_cvt_pk_bf16_f32 v28, v28, s0
	v_cvt_pk_bf16_f32 v24, v24, s0
	v_cvt_pk_bf16_f32 v20, v20, s0
	v_cvt_pk_bf16_f32 v16, v16, s0
	v_cvt_pk_bf16_f32 v8, v8, s0
	v_cvt_pk_bf16_f32 v0, v0, s0
	ds_write_b16 v64, v60 offset:33312
	v_max_f32_e32 v60, v63, v63
	ds_write_b16 v64, v56 offset:33344
	v_max_f32_e32 v56, v59, v59
	ds_write_b16 v64, v52 offset:33376
	v_max_f32_e32 v52, v55, v55
	ds_write_b16 v64, v48 offset:33408
	v_max_f32_e32 v48, v51, v51
	ds_write_b16 v64, v44 offset:37664
	v_max_f32_e32 v44, v47, v47
	ds_write_b16 v64, v40 offset:37696
	v_max_f32_e32 v40, v43, v43
	ds_write_b16 v64, v36 offset:37728
	v_max_f32_e32 v36, v39, v39
	ds_write_b16 v64, v32 offset:37760
	v_max_f32_e32 v32, v35, v35
	ds_write_b16 v64, v28 offset:42016
	v_max_f32_e32 v28, v31, v31
	ds_write_b16 v64, v24 offset:42048
	v_max_f32_e32 v24, v27, v27
	ds_write_b16 v64, v20 offset:42080
	v_max_f32_e32 v20, v23, v23
	ds_write_b16 v64, v16 offset:42112
	v_max_f32_e32 v16, v19, v19
	ds_write_b16 v64, v8 offset:46368
	v_max_f32_e32 v8, v11, v11
	ds_write_b16 v64, v0 offset:46464
	v_max_f32_e32 v0, v7, v7
	s_lshl_b64 s[8:9], s[26:27], 13
	v_max_f32_e32 v60, 0, v60
	v_max_f32_e32 v56, 0, v56
	v_max_f32_e32 v52, 0, v52
	v_max_f32_e32 v48, 0, v48
	v_max_f32_e32 v44, 0, v44
	v_max_f32_e32 v40, 0, v40
	v_max_f32_e32 v36, 0, v36
	v_max_f32_e32 v32, 0, v32
	v_max_f32_e32 v28, 0, v28
	v_max_f32_e32 v24, 0, v24
	v_max_f32_e32 v20, 0, v20
	v_max_f32_e32 v16, 0, v16
	v_max_f32_e32 v8, 0, v8
	v_max_f32_e32 v0, 0, v0
	s_add_u32 s14, s44, s8
	v_mul_f32_e32 v60, v60, v60
	v_mul_f32_e32 v56, v56, v56
	v_mul_f32_e32 v52, v52, v52
	v_mul_f32_e32 v48, v48, v48
	v_mul_f32_e32 v44, v44, v44
	v_mul_f32_e32 v40, v40, v40
	v_mul_f32_e32 v36, v36, v36
	v_mul_f32_e32 v32, v32, v32
	v_mul_f32_e32 v28, v28, v28
	v_mul_f32_e32 v24, v24, v24
	v_mul_f32_e32 v20, v20, v20
	v_mul_f32_e32 v16, v16, v16
	v_mul_f32_e32 v8, v8, v8
	v_mul_f32_e32 v0, v0, v0
	s_addc_u32 s15, s45, s9
	s_lshl_b64 s[8:9], s[20:21], 8
	v_cvt_pk_bf16_f32 v60, v60, s0
	v_cvt_pk_bf16_f32 v56, v56, s0
	v_cvt_pk_bf16_f32 v52, v52, s0
	v_cvt_pk_bf16_f32 v48, v48, s0
	v_cvt_pk_bf16_f32 v44, v44, s0
	v_cvt_pk_bf16_f32 v40, v40, s0
	v_cvt_pk_bf16_f32 v36, v36, s0
	v_cvt_pk_bf16_f32 v32, v32, s0
	v_cvt_pk_bf16_f32 v28, v28, s0
	v_cvt_pk_bf16_f32 v24, v24, s0
	v_cvt_pk_bf16_f32 v20, v20, s0
	v_cvt_pk_bf16_f32 v16, v16, s0
	v_cvt_pk_bf16_f32 v8, v8, s0
	v_cvt_pk_bf16_f32 v0, v0, s0
	v_mov_b32_e32 v14, v254
	s_add_u32 s8, s14, s8
	ds_write_b16 v64, v60 offset:33584
	ds_write_b16 v64, v56 offset:33616
	ds_write_b16 v64, v52 offset:33648
	ds_write_b16 v64, v48 offset:33680
	ds_write_b16 v64, v44 offset:37936
	ds_write_b16 v64, v40 offset:37968
	ds_write_b16 v64, v36 offset:38000
	ds_write_b16 v64, v32 offset:38032
	ds_write_b16 v64, v28 offset:42288
	ds_write_b16 v64, v24 offset:42320
	ds_write_b16 v64, v20 offset:42352
	ds_write_b16 v64, v16 offset:42384
	ds_write_b16 v64, v8 offset:46640
	ds_write_b16 v64, v0 offset:46736
	s_waitcnt lgkmcnt(0)
	s_barrier
	s_addc_u32 s9, s15, s9
	v_lshlrev_b32_e32 v0, 4, v14
	v_ashrrev_i32_e32 v4, 4, v14
	v_and_b32_e32 v148, 0xf0, v0
	v_ashrrev_i32_e32 v5, 31, v4
	v_and_b32_e32 v8, 0x70, v0
	v_and_b32_e32 v9, 0x80, v0
	v_lshl_or_b32 v8, v9, 7, v8
	v_mov_b32_e32 v9, 0
	v_lshl_add_u64 v[8:9], s[8:9], 0, v[8:9]
	v_mad_u64_u32 v[0:1], s[8:9], v4, s42, v[148:149]
	v_lshlrev_b64 v[4:5], 7, v[4:5]
	v_lshl_add_u64 v[10:11], v[8:9], 0, v[4:5]
	v_add_u32_e32 v4, 0x100, v14
	ds_read_b128 v[0:3], v0 offset:32768
	v_ashrrev_i32_e32 v12, 4, v4
	v_mad_u64_u32 v[4:5], s[8:9], v12, s42, v[148:149]
	ds_read_b128 v[4:7], v4 offset:32768
	v_ashrrev_i32_e32 v13, 31, v12
	s_waitcnt lgkmcnt(1)
	global_store_dwordx4 v[10:11], v[0:3], off sc1
	s_and_b64 vcc, exec, s[6:7]
	s_mov_b32 s14, s46
	v_lshlrev_b64 v[0:1], 7, v[12:13]
	v_lshl_add_u64 v[0:1], v[8:9], 0, v[0:1]
	s_waitcnt lgkmcnt(0)
	global_store_dwordx4 v[0:1], v[4:7], off sc1
	v_add_u32_e32 v0, 0x200, v14
	s_nop 0
	v_ashrrev_i32_e32 v4, 4, v0
	v_ashrrev_i32_e32 v5, 31, v4
	v_mad_u64_u32 v[0:1], s[8:9], v4, s42, v[148:149]
	v_lshlrev_b64 v[4:5], 7, v[4:5]
	v_lshl_add_u64 v[10:11], v[8:9], 0, v[4:5]
	v_add_u32_e32 v4, 0x300, v14
	ds_read_b128 v[0:3], v0 offset:32768
	v_ashrrev_i32_e32 v12, 4, v4
	v_mad_u64_u32 v[4:5], s[8:9], v12, s42, v[148:149]
	ds_read_b128 v[4:7], v4 offset:32768
	v_ashrrev_i32_e32 v13, 31, v12
	s_waitcnt lgkmcnt(1)
	global_store_dwordx4 v[10:11], v[0:3], off sc1
	s_nop 1
	v_lshlrev_b64 v[0:1], 7, v[12:13]
	v_lshl_add_u64 v[0:1], v[8:9], 0, v[0:1]
	s_waitcnt lgkmcnt(0)
	global_store_dwordx4 v[0:1], v[4:7], off sc1
	v_add_u32_e32 v0, 0x400, v14
	s_nop 0
	v_ashrrev_i32_e32 v4, 4, v0
	v_ashrrev_i32_e32 v5, 31, v4
	v_mad_u64_u32 v[0:1], s[8:9], v4, s42, v[148:149]
	v_lshlrev_b64 v[4:5], 7, v[4:5]
	v_lshl_add_u64 v[10:11], v[8:9], 0, v[4:5]
	v_add_u32_e32 v4, 0x500, v14
	ds_read_b128 v[0:3], v0 offset:32768
	v_ashrrev_i32_e32 v12, 4, v4
	v_mad_u64_u32 v[4:5], s[8:9], v12, s42, v[148:149]
	ds_read_b128 v[4:7], v4 offset:32768
	v_ashrrev_i32_e32 v13, 31, v12
	s_waitcnt lgkmcnt(1)
	global_store_dwordx4 v[10:11], v[0:3], off sc1
	s_nop 1
	v_lshlrev_b64 v[0:1], 7, v[12:13]
	v_lshl_add_u64 v[0:1], v[8:9], 0, v[0:1]
	s_waitcnt lgkmcnt(0)
	global_store_dwordx4 v[0:1], v[4:7], off sc1
	v_add_u32_e32 v0, 0x600, v14
	s_nop 0
	v_ashrrev_i32_e32 v4, 4, v0
	v_ashrrev_i32_e32 v5, 31, v4
	v_mad_u64_u32 v[0:1], s[8:9], v4, s42, v[148:149]
	v_lshlrev_b64 v[4:5], 7, v[4:5]
	v_lshl_add_u64 v[10:11], v[8:9], 0, v[4:5]
	v_add_u32_e32 v4, 0x700, v14
	ds_read_b128 v[0:3], v0 offset:32768
	v_ashrrev_i32_e32 v12, 4, v4
	v_mad_u64_u32 v[4:5], s[8:9], v12, s42, v[148:149]
	ds_read_b128 v[4:7], v4 offset:32768
	v_ashrrev_i32_e32 v13, 31, v12
	s_waitcnt lgkmcnt(1)
	global_store_dwordx4 v[10:11], v[0:3], off sc1
	s_mov_b64 s[8:9], -1
	s_nop 0
	v_lshlrev_b64 v[0:1], 7, v[12:13]
	v_lshl_add_u64 v[0:1], v[8:9], 0, v[0:1]
	s_waitcnt lgkmcnt(0)
	global_store_dwordx4 v[0:1], v[4:7], off sc1
	s_cbranch_vccnz .LBB0_199
